# xattn: V-image LDS-DMA issued right after the last QK MFMA (behind the K-image-free barrier) so it flies under the softmax
# baseline (speedup 1.0000x reference)
; #define LAS __attribute__((address_space(3)))
; __device__ __forceinline__ void glds16(const void* gsrc, LAS unsigned char* dst_uniform) { __builtin_amdgcn_global_load_lds((const unsigned*)gsrc, (LAS unsigned*)dst_uniform, 16, 0, 0); }
; #define ATT_SYNC() do { asm volatile("s_waitcnt vmcnt(0) lgkmcnt(0)" ::: "memory"); __syncthreads(); } while (0)
; __device__ __forceinline__ void xattn_unit(LAS unsigned char* lds, const bf16_t* Qx, const bf16_t* KV, int li, int b, int h, int qb, bf16_t* XO, const int tid) {
;     ...
; #pragma unroll 4
;     for (int ii = 0; ii < 16; ++ii) { const int i = wid * 16 + ii, key = 2 * i + hi, c = r32 ^ (key & 15);
;         glds16(Kb + (size_t)key * 8192 + c * 8, lds + i * 1024); }
;     bf16x8 qf[16]; { const bf16_t* qp = Qx + tok * 1024 + h * 256 + hi * 8;
; #pragma unroll
;         for (int s = 0; s < 16; ++s) qf[s] = *(const bf16x8*)(qp + 16 * s); }
;     ATT_SYNC();
;     f32x16 S[8];
; #pragma unroll
;     for (int kt = 0; kt < 8; ++kt) { f32x16 acc = {}; const lds_cptr kp = (lds_cptr)lds + (32 * kt + r32) * 512;
; #pragma unroll
;         for (int s = 0; s < 16; ++s) { const bf16x8 kf = *(const LAS bf16x8*)(kp + (((2 * s + hi) ^ (r32 & 15)) << 4)); acc = __builtin_amdgcn_mfma_f32_32x32x16_bf16(kf, qf[s], acc, 0, 0, 0); }
;         S[kt] = acc; }
.LBB0_432:
	v_add_u32_e32 v1, -6, v0
	v_bitop3_b32 v1, v1, v203, 9 bitop3:0x6c
	v_lshlrev_b32_e32 v208, 4, v1
	v_lshl_add_u64 v[10:11], v[8:9], 0, s[18:19]
	s_add_i32 s26, s24, s25
	v_add_u32_e32 v1, -4, v0
	v_lshl_add_u64 v[10:11], v[10:11], 0, v[208:209]
	s_mov_b32 m0, s26
	v_bitop3_b32 v1, v1, v203, 11 bitop3:0x6c
	global_load_lds_dwordx4 v[10:11], off
	v_lshlrev_b32_e32 v208, 4, v1
	v_lshl_add_u64 v[10:11], v[6:7], 0, s[18:19]
	v_add_u32_e32 v1, -2, v0
	v_lshl_add_u64 v[10:11], v[10:11], 0, v[208:209]
	s_add_i32 m0, s26, 0x400
	v_bitop3_b32 v1, v1, v203, 13 bitop3:0x6c
	global_load_lds_dwordx4 v[10:11], off
	v_lshlrev_b32_e32 v208, 4, v1
	v_lshl_add_u64 v[10:11], v[4:5], 0, s[18:19]
	v_lshl_add_u64 v[10:11], v[10:11], 0, v[208:209]
	s_add_i32 m0, s26, 0x800
	v_bitop3_b32 v1, v0, v203, 15 bitop3:0x6c
	global_load_lds_dwordx4 v[10:11], off
	v_lshlrev_b32_e32 v208, 4, v1
	v_lshl_add_u64 v[10:11], v[2:3], 0, s[18:19]
	v_lshl_add_u64 v[10:11], v[10:11], 0, v[208:209]
	s_add_i32 m0, s26, 0xc00
	s_addk_i32 s25, 0x1000
	global_load_lds_dwordx4 v[10:11], off
	v_lshl_add_u64 v[2:3], v[2:3], 0, s[28:29]
	v_add_u32_e32 v0, 8, v0
	v_lshl_add_u64 v[4:5], v[4:5], 0, s[28:29]
	v_lshl_add_u64 v[6:7], v[6:7], 0, s[28:29]
	v_lshl_add_u64 v[8:9], v[8:9], 0, s[28:29]
	s_cmpk_eq_i32 s25, 0x4000
	s_cbranch_scc0 .LBB0_432
	s_lshl_b32 s25, s30, 8
	s_and_b32 s25, s25, 0xf00
	s_lshl_b64 s[0:1], s[0:1], 12
	v_or_b32_e32 v0, s25, v203
	s_ashr_i32 s37, s36, 31
	v_or_b32_e32 v0, s0, v0
	v_mov_b32_e32 v1, s1
	v_lshl_add_u64 v[0:1], v[0:1], 0, s[36:37]
	v_lshlrev_b64 v[200:201], 10, v[0:1]
	v_lshlrev_b64 v[0:1], 11, v[0:1]
	v_lshl_add_u64 v[0:1], s[8:9], 0, v[0:1]
	v_lshl_add_u64 v[0:1], s[12:13], 1, v[0:1]
	v_mov_b32_e32 v197, v209
	v_lshl_add_u64 v[0:1], v[0:1], 0, v[196:197]
	global_load_dwordx4 v[112:115], v[0:1], off
	global_load_dwordx4 v[184:187], v[0:1], off offset:32
	global_load_dwordx4 v[180:183], v[0:1], off offset:64
	global_load_dwordx4 v[176:179], v[0:1], off offset:96
	global_load_dwordx4 v[172:175], v[0:1], off offset:128
	global_load_dwordx4 v[168:171], v[0:1], off offset:160
	global_load_dwordx4 v[164:167], v[0:1], off offset:192
	global_load_dwordx4 v[160:163], v[0:1], off offset:224
	global_load_dwordx4 v[156:159], v[0:1], off offset:256
	global_load_dwordx4 v[152:155], v[0:1], off offset:288
	global_load_dwordx4 v[148:151], v[0:1], off offset:320
	global_load_dwordx4 v[144:147], v[0:1], off offset:352
	global_load_dwordx4 v[140:143], v[0:1], off offset:384
	global_load_dwordx4 v[136:139], v[0:1], off offset:416
	global_load_dwordx4 v[132:135], v[0:1], off offset:448
	global_load_dwordx4 v[128:131], v[0:1], off offset:480
	v_add_u32_e32 v32, v205, v206
	s_waitcnt vmcnt(0) lgkmcnt(0)
	s_waitcnt vmcnt(0) lgkmcnt(0)
	s_barrier
	ds_read_b128 v[0:3], v32
	v_add_u32_e32 v78, v205, v207
	ds_read_b128 v[16:19], v78
	v_add_u32_e32 v77, v205, v211
	v_add_u32_e32 v76, v205, v212
	v_add_u32_e32 v75, v205, v218
	v_add_u32_e32 v74, v205, v219
	v_add_u32_e32 v73, v205, v220
	v_add_u32_e32 v72, v205, v221
	v_add_u32_e32 v71, v205, v237
	v_add_u32_e32 v70, v205, v238
	v_add_u32_e32 v69, v205, v239
	v_add_u32_e32 v68, v205, v240
	v_add_u32_e32 v67, v205, v241
	v_add_u32_e32 v66, v205, v242
	v_add_u32_e32 v65, v205, v243
	v_add_u32_e32 v64, v205, v244
	v_add_u32_e32 v197, v248, v207
	v_add_u32_e32 v96, v246, v207
	v_add_u32_e32 v116, v247, v207
	s_add_u32 s14, s14, s18
	s_addc_u32 s15, s15, s19
	s_lshl_b64 s[0:1], s[36:37], 1
	s_add_u32 s0, s14, s0
	s_addc_u32 s1, s15, s1
	s_waitcnt lgkmcnt(1)
	v_mfma_f32_32x32x16_bf16 v[0:15], v[0:3], v[112:115], 0
	ds_read_b128 v[222:225], v197
	ds_read_b128 v[34:37], v78 offset:16384
	ds_read_b128 v[96:99], v96
	ds_read_b128 v[116:119], v116
	s_waitcnt lgkmcnt(4)
	v_mfma_f32_32x32x16_bf16 v[0:15], v[16:19], v[184:187], v[0:15]
	ds_read_b128 v[16:19], v77
	s_waitcnt lgkmcnt(0)
	v_mfma_f32_32x32x16_bf16 v[0:15], v[16:19], v[180:183], v[0:15]
	ds_read_b128 v[16:19], v76
	s_waitcnt lgkmcnt(0)
	v_mfma_f32_32x32x16_bf16 v[0:15], v[16:19], v[176:179], v[0:15]
	ds_read_b128 v[16:19], v75
	s_waitcnt lgkmcnt(0)
	v_mfma_f32_32x32x16_bf16 v[0:15], v[16:19], v[172:175], v[0:15]
	ds_read_b128 v[16:19], v74
	s_waitcnt lgkmcnt(0)
	v_mfma_f32_32x32x16_bf16 v[0:15], v[16:19], v[168:171], v[0:15]
	ds_read_b128 v[16:19], v73
	s_waitcnt lgkmcnt(0)
	v_mfma_f32_32x32x16_bf16 v[0:15], v[16:19], v[164:167], v[0:15]
	ds_read_b128 v[16:19], v72
	s_waitcnt lgkmcnt(0)
	v_mfma_f32_32x32x16_bf16 v[0:15], v[16:19], v[160:163], v[0:15]
	ds_read_b128 v[16:19], v71
	s_waitcnt lgkmcnt(0)
	v_mfma_f32_32x32x16_bf16 v[0:15], v[16:19], v[156:159], v[0:15]
	ds_read_b128 v[16:19], v70
	s_waitcnt lgkmcnt(0)
	v_mfma_f32_32x32x16_bf16 v[0:15], v[16:19], v[152:155], v[0:15]
	ds_read_b128 v[16:19], v69
	s_waitcnt lgkmcnt(0)
	v_mfma_f32_32x32x16_bf16 v[0:15], v[16:19], v[148:151], v[0:15]
	ds_read_b128 v[16:19], v68
	s_waitcnt lgkmcnt(0)
	v_mfma_f32_32x32x16_bf16 v[0:15], v[16:19], v[144:147], v[0:15]
	ds_read_b128 v[16:19], v67
	s_waitcnt lgkmcnt(0)
	v_mfma_f32_32x32x16_bf16 v[0:15], v[16:19], v[140:143], v[0:15]
	ds_read_b128 v[16:19], v66
	s_waitcnt lgkmcnt(0)
	v_mfma_f32_32x32x16_bf16 v[0:15], v[16:19], v[136:139], v[0:15]
	ds_read_b128 v[16:19], v65
	s_waitcnt lgkmcnt(0)
	v_mfma_f32_32x32x16_bf16 v[0:15], v[16:19], v[132:135], v[0:15]
	ds_read_b128 v[16:19], v64
	s_waitcnt lgkmcnt(0)
	v_mfma_f32_32x32x16_bf16 v[0:15], v[16:19], v[128:131], v[0:15]
	ds_read_b128 v[16:19], v32 offset:16384
	s_waitcnt lgkmcnt(0)
	v_mfma_f32_32x32x16_bf16 v[16:31], v[16:19], v[112:115], 0
	v_mfma_f32_32x32x16_bf16 v[16:31], v[34:37], v[184:187], v[16:31]
	ds_read_b128 v[34:37], v77 offset:16384
	s_waitcnt lgkmcnt(0)
; #define LAS __attribute__((address_space(3)))
; __device__ __forceinline__ void xattn_unit(LAS unsigned char* lds, const bf16_t* Qx, const bf16_t* KV, int li, int b, int h, int qb, bf16_t* XO, const int tid) {
;     ...
;     for (int kt = 0; kt < 8; ++kt) { f32x16 acc = {}; const lds_cptr kp = (lds_cptr)lds + (32 * kt + r32) * 512;
; #pragma unroll
;         for (int s = 0; s < 16; ++s) { const bf16x8 kf = *(const LAS bf16x8*)(kp + (((2 * s + hi) ^ (r32 & 15)) << 4)); acc = __builtin_amdgcn_mfma_f32_32x32x16_bf16(kf, qf[s], acc, 0, 0, 0); }
;         S[kt] = acc; }
	v_mfma_f32_32x32x16_bf16 v[16:31], v[34:37], v[180:183], v[16:31]
	ds_read_b128 v[34:37], v76 offset:16384
	s_waitcnt lgkmcnt(0)
	v_mfma_f32_32x32x16_bf16 v[16:31], v[34:37], v[176:179], v[16:31]
	ds_read_b128 v[34:37], v75 offset:16384
	s_waitcnt lgkmcnt(0)
	v_mfma_f32_32x32x16_bf16 v[16:31], v[34:37], v[172:175], v[16:31]
	ds_read_b128 v[34:37], v74 offset:16384
	s_waitcnt lgkmcnt(0)
	v_mfma_f32_32x32x16_bf16 v[16:31], v[34:37], v[168:171], v[16:31]
	ds_read_b128 v[34:37], v73 offset:16384
	s_waitcnt lgkmcnt(0)
	v_mfma_f32_32x32x16_bf16 v[16:31], v[34:37], v[164:167], v[16:31]
	ds_read_b128 v[34:37], v72 offset:16384
	s_waitcnt lgkmcnt(0)
	v_mfma_f32_32x32x16_bf16 v[16:31], v[34:37], v[160:163], v[16:31]
	ds_read_b128 v[34:37], v71 offset:16384
	s_waitcnt lgkmcnt(0)
	v_mfma_f32_32x32x16_bf16 v[16:31], v[34:37], v[156:159], v[16:31]
	ds_read_b128 v[34:37], v70 offset:16384
	s_waitcnt lgkmcnt(0)
	v_mfma_f32_32x32x16_bf16 v[16:31], v[34:37], v[152:155], v[16:31]
	ds_read_b128 v[34:37], v69 offset:16384
	s_waitcnt lgkmcnt(0)
	v_mfma_f32_32x32x16_bf16 v[16:31], v[34:37], v[148:151], v[16:31]
	ds_read_b128 v[34:37], v68 offset:16384
	s_waitcnt lgkmcnt(0)
	v_mfma_f32_32x32x16_bf16 v[16:31], v[34:37], v[144:147], v[16:31]
	ds_read_b128 v[34:37], v67 offset:16384
	s_waitcnt lgkmcnt(0)
	v_mfma_f32_32x32x16_bf16 v[16:31], v[34:37], v[140:143], v[16:31]
	ds_read_b128 v[34:37], v66 offset:16384
	s_waitcnt lgkmcnt(0)
	v_mfma_f32_32x32x16_bf16 v[16:31], v[34:37], v[136:139], v[16:31]
	ds_read_b128 v[34:37], v65 offset:16384
	s_waitcnt lgkmcnt(0)
	v_mfma_f32_32x32x16_bf16 v[16:31], v[34:37], v[132:135], v[16:31]
	ds_read_b128 v[34:37], v64 offset:16384
	s_waitcnt lgkmcnt(0)
	v_mfma_f32_32x32x16_bf16 v[16:31], v[34:37], v[128:131], v[16:31]
	ds_read_b128 v[34:37], v32 offset:32768
	s_waitcnt lgkmcnt(0)
	v_mfma_f32_32x32x16_bf16 v[48:63], v[34:37], v[112:115], 0
	ds_read_b128 v[34:37], v78 offset:32768
	ds_read_b128 v[78:81], v78 offset:49152
	s_waitcnt lgkmcnt(1)
	v_mfma_f32_32x32x16_bf16 v[48:63], v[34:37], v[184:187], v[48:63]
	ds_read_b128 v[34:37], v77 offset:32768
	s_waitcnt lgkmcnt(0)
	v_mfma_f32_32x32x16_bf16 v[48:63], v[34:37], v[180:183], v[48:63]
	ds_read_b128 v[34:37], v76 offset:32768
	s_waitcnt lgkmcnt(0)
	v_mfma_f32_32x32x16_bf16 v[48:63], v[34:37], v[176:179], v[48:63]
	ds_read_b128 v[34:37], v75 offset:32768
	s_waitcnt lgkmcnt(0)
	v_mfma_f32_32x32x16_bf16 v[48:63], v[34:37], v[172:175], v[48:63]
	ds_read_b128 v[34:37], v74 offset:32768
	s_waitcnt lgkmcnt(0)
	v_mfma_f32_32x32x16_bf16 v[48:63], v[34:37], v[168:171], v[48:63]
	ds_read_b128 v[34:37], v73 offset:32768
	s_waitcnt lgkmcnt(0)
	v_mfma_f32_32x32x16_bf16 v[48:63], v[34:37], v[164:167], v[48:63]
	ds_read_b128 v[34:37], v72 offset:32768
	s_waitcnt lgkmcnt(0)
	v_mfma_f32_32x32x16_bf16 v[48:63], v[34:37], v[160:163], v[48:63]
	ds_read_b128 v[34:37], v71 offset:32768
	s_waitcnt lgkmcnt(0)
	v_mfma_f32_32x32x16_bf16 v[48:63], v[34:37], v[156:159], v[48:63]
	ds_read_b128 v[34:37], v70 offset:32768
	s_waitcnt lgkmcnt(0)
	v_mfma_f32_32x32x16_bf16 v[48:63], v[34:37], v[152:155], v[48:63]
	ds_read_b128 v[34:37], v69 offset:32768
	s_waitcnt lgkmcnt(0)
	v_mfma_f32_32x32x16_bf16 v[48:63], v[34:37], v[148:151], v[48:63]
	ds_read_b128 v[34:37], v68 offset:32768
	s_waitcnt lgkmcnt(0)
	v_mfma_f32_32x32x16_bf16 v[48:63], v[34:37], v[144:147], v[48:63]
	ds_read_b128 v[34:37], v67 offset:32768
	s_waitcnt lgkmcnt(0)
	v_mfma_f32_32x32x16_bf16 v[48:63], v[34:37], v[140:143], v[48:63]
	ds_read_b128 v[34:37], v66 offset:32768
	s_waitcnt lgkmcnt(0)
	v_mfma_f32_32x32x16_bf16 v[48:63], v[34:37], v[136:139], v[48:63]
	ds_read_b128 v[34:37], v65 offset:32768
	s_waitcnt lgkmcnt(0)
	v_mfma_f32_32x32x16_bf16 v[48:63], v[34:37], v[132:135], v[48:63]
	ds_read_b128 v[34:37], v64 offset:32768
	s_waitcnt lgkmcnt(0)
	v_mfma_f32_32x32x16_bf16 v[48:63], v[34:37], v[128:131], v[48:63]
	ds_read_b128 v[32:35], v32 offset:49152
	s_waitcnt lgkmcnt(0)
	v_mfma_f32_32x32x16_bf16 v[32:47], v[32:35], v[112:115], 0
	v_mfma_f32_32x32x16_bf16 v[32:47], v[78:81], v[184:187], v[32:47]
	ds_read_b128 v[78:81], v77 offset:49152
	s_waitcnt lgkmcnt(0)
	v_mfma_f32_32x32x16_bf16 v[32:47], v[78:81], v[180:183], v[32:47]
	ds_read_b128 v[76:79], v76 offset:49152
	v_add_u32_e32 v80, v245, v207
	ds_read_b128 v[80:83], v80
	s_waitcnt lgkmcnt(1)
	v_mfma_f32_32x32x16_bf16 v[32:47], v[76:79], v[176:179], v[32:47]
	ds_read_b128 v[76:79], v75 offset:49152
	s_waitcnt lgkmcnt(0)
	v_mfma_f32_32x32x16_bf16 v[32:47], v[76:79], v[172:175], v[32:47]
	ds_read_b128 v[74:77], v74 offset:49152
	s_waitcnt lgkmcnt(0)
	v_mfma_f32_32x32x16_bf16 v[32:47], v[74:77], v[168:171], v[32:47]
	ds_read_b128 v[74:77], v73 offset:49152
	s_waitcnt lgkmcnt(0)
	v_mfma_f32_32x32x16_bf16 v[32:47], v[74:77], v[164:167], v[32:47]
	ds_read_b128 v[72:75], v72 offset:49152
	s_waitcnt lgkmcnt(0)
	v_mfma_f32_32x32x16_bf16 v[32:47], v[72:75], v[160:163], v[32:47]
	ds_read_b128 v[72:75], v71 offset:49152
	s_waitcnt lgkmcnt(0)
	v_mfma_f32_32x32x16_bf16 v[32:47], v[72:75], v[156:159], v[32:47]
	ds_read_b128 v[70:73], v70 offset:49152
	s_waitcnt lgkmcnt(0)
	v_mfma_f32_32x32x16_bf16 v[32:47], v[70:73], v[152:155], v[32:47]
	ds_read_b128 v[70:73], v69 offset:49152
	s_waitcnt lgkmcnt(0)
	v_mfma_f32_32x32x16_bf16 v[32:47], v[70:73], v[148:151], v[32:47]
	ds_read_b128 v[68:71], v68 offset:49152
	s_waitcnt lgkmcnt(0)
	v_mfma_f32_32x32x16_bf16 v[32:47], v[68:71], v[144:147], v[32:47]
	ds_read_b128 v[68:71], v67 offset:49152
	s_waitcnt lgkmcnt(0)
	v_mfma_f32_32x32x16_bf16 v[32:47], v[68:71], v[140:143], v[32:47]
	ds_read_b128 v[66:69], v66 offset:49152
	s_waitcnt lgkmcnt(0)
; #define LAS __attribute__((address_space(3)))
; __device__ __forceinline__ void xattn_unit(LAS unsigned char* lds, const bf16_t* Qx, const bf16_t* KV, int li, int b, int h, int qb, bf16_t* XO, const int tid) {
;     ...
;     for (int kt = 0; kt < 8; ++kt) { f32x16 acc = {}; const lds_cptr kp = (lds_cptr)lds + (32 * kt + r32) * 512;
; #pragma unroll
;         for (int s = 0; s < 16; ++s) { const bf16x8 kf = *(const LAS bf16x8*)(kp + (((2 * s + hi) ^ (r32 & 15)) << 4)); acc = __builtin_amdgcn_mfma_f32_32x32x16_bf16(kf, qf[s], acc, 0, 0, 0); }
;         S[kt] = acc; }
	v_mfma_f32_32x32x16_bf16 v[32:47], v[66:69], v[136:139], v[32:47]
	ds_read_b128 v[66:69], v65 offset:49152
	s_waitcnt lgkmcnt(0)
	v_mfma_f32_32x32x16_bf16 v[32:47], v[66:69], v[132:135], v[32:47]
	ds_read_b128 v[64:67], v64 offset:49152
	s_waitcnt lgkmcnt(0)
	v_mfma_f32_32x32x16_bf16 v[32:47], v[64:67], v[128:131], v[32:47]
	v_add_u32_e32 v64, v245, v206
	ds_read_b128 v[64:67], v64
	s_waitcnt lgkmcnt(0)
	v_mfma_f32_32x32x16_bf16 v[64:79], v[64:67], v[112:115], 0
	v_mfma_f32_32x32x16_bf16 v[64:79], v[80:83], v[184:187], v[64:79]
	v_add_u32_e32 v80, v245, v211
	ds_read_b128 v[80:83], v80
	s_waitcnt lgkmcnt(0)
	v_mfma_f32_32x32x16_bf16 v[64:79], v[80:83], v[180:183], v[64:79]
	v_add_u32_e32 v80, v245, v212
	ds_read_b128 v[80:83], v80
	s_waitcnt lgkmcnt(0)
	v_mfma_f32_32x32x16_bf16 v[64:79], v[80:83], v[176:179], v[64:79]
	v_add_u32_e32 v80, v245, v218
	ds_read_b128 v[80:83], v80
	s_waitcnt lgkmcnt(0)
	v_mfma_f32_32x32x16_bf16 v[64:79], v[80:83], v[172:175], v[64:79]
	v_add_u32_e32 v80, v245, v219
	ds_read_b128 v[80:83], v80
	s_waitcnt lgkmcnt(0)
	v_mfma_f32_32x32x16_bf16 v[64:79], v[80:83], v[168:171], v[64:79]
	v_add_u32_e32 v80, v245, v220
	ds_read_b128 v[80:83], v80
	s_waitcnt lgkmcnt(0)
	v_mfma_f32_32x32x16_bf16 v[64:79], v[80:83], v[164:167], v[64:79]
	v_add_u32_e32 v80, v245, v221
	ds_read_b128 v[80:83], v80
	s_waitcnt lgkmcnt(0)
	v_mfma_f32_32x32x16_bf16 v[64:79], v[80:83], v[160:163], v[64:79]
	v_add_u32_e32 v80, v245, v237
	ds_read_b128 v[80:83], v80
	s_waitcnt lgkmcnt(0)
	v_mfma_f32_32x32x16_bf16 v[64:79], v[80:83], v[156:159], v[64:79]
	v_add_u32_e32 v80, v245, v238
	ds_read_b128 v[80:83], v80
	s_waitcnt lgkmcnt(0)
	v_mfma_f32_32x32x16_bf16 v[64:79], v[80:83], v[152:155], v[64:79]
	v_add_u32_e32 v80, v245, v239
	ds_read_b128 v[80:83], v80
	s_waitcnt lgkmcnt(0)
	v_mfma_f32_32x32x16_bf16 v[64:79], v[80:83], v[148:151], v[64:79]
	v_add_u32_e32 v80, v245, v240
	ds_read_b128 v[80:83], v80
	s_waitcnt lgkmcnt(0)
	v_mfma_f32_32x32x16_bf16 v[64:79], v[80:83], v[144:147], v[64:79]
	v_add_u32_e32 v80, v245, v241
	ds_read_b128 v[80:83], v80
	s_waitcnt lgkmcnt(0)
	v_mfma_f32_32x32x16_bf16 v[64:79], v[80:83], v[140:143], v[64:79]
	v_add_u32_e32 v80, v245, v242
	ds_read_b128 v[80:83], v80
	s_waitcnt lgkmcnt(0)
	v_mfma_f32_32x32x16_bf16 v[64:79], v[80:83], v[136:139], v[64:79]
	v_add_u32_e32 v80, v245, v243
	ds_read_b128 v[80:83], v80
	s_waitcnt lgkmcnt(0)
	v_mfma_f32_32x32x16_bf16 v[64:79], v[80:83], v[132:135], v[64:79]
	v_add_u32_e32 v80, v245, v244
	ds_read_b128 v[80:83], v80
	s_waitcnt lgkmcnt(0)
	v_mfma_f32_32x32x16_bf16 v[64:79], v[80:83], v[128:131], v[64:79]
	v_add_u32_e32 v80, v246, v206
	ds_read_b128 v[80:83], v80
	s_waitcnt lgkmcnt(0)
	v_mfma_f32_32x32x16_bf16 v[80:95], v[80:83], v[112:115], 0
	v_mfma_f32_32x32x16_bf16 v[80:95], v[96:99], v[184:187], v[80:95]
	v_add_u32_e32 v96, v246, v211
	ds_read_b128 v[96:99], v96
	s_waitcnt lgkmcnt(0)
	v_mfma_f32_32x32x16_bf16 v[80:95], v[96:99], v[180:183], v[80:95]
	v_add_u32_e32 v96, v246, v212
	ds_read_b128 v[96:99], v96
	s_waitcnt lgkmcnt(0)
	v_mfma_f32_32x32x16_bf16 v[80:95], v[96:99], v[176:179], v[80:95]
	v_add_u32_e32 v96, v246, v218
	ds_read_b128 v[96:99], v96
	s_waitcnt lgkmcnt(0)
	v_mfma_f32_32x32x16_bf16 v[80:95], v[96:99], v[172:175], v[80:95]
	v_add_u32_e32 v96, v246, v219
	ds_read_b128 v[96:99], v96
	s_waitcnt lgkmcnt(0)
	v_mfma_f32_32x32x16_bf16 v[80:95], v[96:99], v[168:171], v[80:95]
	v_add_u32_e32 v96, v246, v220
	ds_read_b128 v[96:99], v96
	s_waitcnt lgkmcnt(0)
	v_mfma_f32_32x32x16_bf16 v[80:95], v[96:99], v[164:167], v[80:95]
	v_add_u32_e32 v96, v246, v221
	ds_read_b128 v[96:99], v96
	s_waitcnt lgkmcnt(0)
	v_mfma_f32_32x32x16_bf16 v[80:95], v[96:99], v[160:163], v[80:95]
	v_add_u32_e32 v96, v246, v237
	ds_read_b128 v[96:99], v96
	s_waitcnt lgkmcnt(0)
	v_mfma_f32_32x32x16_bf16 v[80:95], v[96:99], v[156:159], v[80:95]
	v_add_u32_e32 v96, v246, v238
	ds_read_b128 v[96:99], v96
	s_waitcnt lgkmcnt(0)
	v_mfma_f32_32x32x16_bf16 v[80:95], v[96:99], v[152:155], v[80:95]
	v_add_u32_e32 v96, v246, v239
	ds_read_b128 v[96:99], v96
	s_waitcnt lgkmcnt(0)
	v_mfma_f32_32x32x16_bf16 v[80:95], v[96:99], v[148:151], v[80:95]
	v_add_u32_e32 v96, v246, v240
	ds_read_b128 v[96:99], v96
	s_waitcnt lgkmcnt(0)
	v_mfma_f32_32x32x16_bf16 v[80:95], v[96:99], v[144:147], v[80:95]
	v_add_u32_e32 v96, v246, v241
	ds_read_b128 v[96:99], v96
	s_waitcnt lgkmcnt(0)
	v_mfma_f32_32x32x16_bf16 v[80:95], v[96:99], v[140:143], v[80:95]
	v_add_u32_e32 v96, v246, v242
	ds_read_b128 v[96:99], v96
	s_waitcnt lgkmcnt(0)
	v_mfma_f32_32x32x16_bf16 v[80:95], v[96:99], v[136:139], v[80:95]
	v_add_u32_e32 v96, v246, v243
	ds_read_b128 v[96:99], v96
	s_waitcnt lgkmcnt(0)
	v_mfma_f32_32x32x16_bf16 v[80:95], v[96:99], v[132:135], v[80:95]
	v_add_u32_e32 v96, v246, v244
	ds_read_b128 v[96:99], v96
	s_waitcnt lgkmcnt(0)
	v_mfma_f32_32x32x16_bf16 v[80:95], v[96:99], v[128:131], v[80:95]
	v_add_u32_e32 v96, v247, v206
	ds_read_b128 v[96:99], v96
	s_waitcnt lgkmcnt(0)
	v_mfma_f32_32x32x16_bf16 v[96:111], v[96:99], v[112:115], 0
	v_mfma_f32_32x32x16_bf16 v[96:111], v[116:119], v[184:187], v[96:111]
	v_add_u32_e32 v116, v247, v211
	ds_read_b128 v[116:119], v116
	s_waitcnt lgkmcnt(0)
	v_mfma_f32_32x32x16_bf16 v[96:111], v[116:119], v[180:183], v[96:111]
	v_add_u32_e32 v116, v247, v212
	ds_read_b128 v[116:119], v116
	s_waitcnt lgkmcnt(0)
	v_mfma_f32_32x32x16_bf16 v[96:111], v[116:119], v[176:179], v[96:111]
	v_add_u32_e32 v116, v247, v218
	ds_read_b128 v[116:119], v116
	s_waitcnt lgkmcnt(0)
	v_mfma_f32_32x32x16_bf16 v[96:111], v[116:119], v[172:175], v[96:111]
	v_add_u32_e32 v116, v247, v219
	ds_read_b128 v[116:119], v116
	s_waitcnt lgkmcnt(0)
; #define LAS __attribute__((address_space(3)))
; __device__ __forceinline__ void glds16(const void* gsrc, LAS unsigned char* dst_uniform) { __builtin_amdgcn_global_load_lds((const unsigned*)gsrc, (LAS unsigned*)dst_uniform, 16, 0, 0); }
; #define ATT_SYNC() do { asm volatile("s_waitcnt vmcnt(0) lgkmcnt(0)" ::: "memory"); __syncthreads(); } while (0)
; __device__ __forceinline__ void xattn_unit(LAS unsigned char* lds, const bf16_t* Qx, const bf16_t* KV, int li, int b, int h, int qb, bf16_t* XO, const int tid) {
;     ...
;     for (int kt = 0; kt < 8; ++kt) { f32x16 acc = {}; const lds_cptr kp = (lds_cptr)lds + (32 * kt + r32) * 512;
; #pragma unroll
;         for (int s = 0; s < 16; ++s) { const bf16x8 kf = *(const LAS bf16x8*)(kp + (((2 * s + hi) ^ (r32 & 15)) << 4)); acc = __builtin_amdgcn_mfma_f32_32x32x16_bf16(kf, qf[s], acc, 0, 0, 0); }
;         S[kt] = acc; }
;     ...
;     ATT_SYNC();
;     const bf16_t* Vb = Kb + 1024;
; #pragma unroll 4
;     for (int ii = 0; ii < 16; ++ii) { const int i = wid * 16 + ii, d0 = i >> 4, ks = i & 15, key = 16 * ks + 8 * hi + ((lane >> 2) & 7), cc = lane & 3;
;         glds16(Vb + (size_t)key * 8192 + 32 * d0 + 8 * cc, lds + i * 1024); }
	v_mfma_f32_32x32x16_bf16 v[96:111], v[116:119], v[168:171], v[96:111]
	v_add_u32_e32 v116, v247, v220
	ds_read_b128 v[116:119], v116
	s_waitcnt lgkmcnt(0)
	v_mfma_f32_32x32x16_bf16 v[96:111], v[116:119], v[164:167], v[96:111]
	v_add_u32_e32 v116, v247, v221
	ds_read_b128 v[116:119], v116
	s_waitcnt lgkmcnt(0)
	v_mfma_f32_32x32x16_bf16 v[96:111], v[116:119], v[160:163], v[96:111]
	v_add_u32_e32 v116, v247, v237
	ds_read_b128 v[116:119], v116
	s_waitcnt lgkmcnt(0)
	v_mfma_f32_32x32x16_bf16 v[96:111], v[116:119], v[156:159], v[96:111]
	v_add_u32_e32 v116, v247, v238
	ds_read_b128 v[116:119], v116
	s_waitcnt lgkmcnt(0)
	v_mfma_f32_32x32x16_bf16 v[96:111], v[116:119], v[152:155], v[96:111]
	v_add_u32_e32 v116, v247, v239
	ds_read_b128 v[116:119], v116
	s_waitcnt lgkmcnt(0)
	v_mfma_f32_32x32x16_bf16 v[96:111], v[116:119], v[148:151], v[96:111]
	v_add_u32_e32 v116, v247, v240
	ds_read_b128 v[116:119], v116
	s_waitcnt lgkmcnt(0)
	v_mfma_f32_32x32x16_bf16 v[96:111], v[116:119], v[144:147], v[96:111]
	v_add_u32_e32 v116, v247, v241
	ds_read_b128 v[116:119], v116
	s_waitcnt lgkmcnt(0)
	v_mfma_f32_32x32x16_bf16 v[96:111], v[116:119], v[140:143], v[96:111]
	v_add_u32_e32 v116, v247, v242
	ds_read_b128 v[116:119], v116
	s_waitcnt lgkmcnt(0)
	v_mfma_f32_32x32x16_bf16 v[96:111], v[116:119], v[136:139], v[96:111]
	v_add_u32_e32 v116, v247, v243
	ds_read_b128 v[116:119], v116
	s_waitcnt lgkmcnt(0)
	v_mfma_f32_32x32x16_bf16 v[96:111], v[116:119], v[132:135], v[96:111]
	v_add_u32_e32 v116, v247, v244
	ds_read_b128 v[116:119], v116
	s_waitcnt lgkmcnt(0)
	v_mfma_f32_32x32x16_bf16 v[96:111], v[116:119], v[128:131], v[96:111]
	v_add_u32_e32 v116, v248, v206
	ds_read_b128 v[116:119], v116
	s_waitcnt lgkmcnt(0)
	v_mfma_f32_32x32x16_bf16 v[112:127], v[116:119], v[112:115], 0
	v_mfma_f32_32x32x16_bf16 v[112:127], v[222:225], v[184:187], v[112:127]
	v_add_u32_e32 v184, v248, v211
	ds_read_b128 v[184:187], v184
	s_waitcnt lgkmcnt(0)
	v_mfma_f32_32x32x16_bf16 v[112:127], v[184:187], v[180:183], v[112:127]
	v_add_u32_e32 v180, v248, v212
	ds_read_b128 v[180:183], v180
	s_waitcnt lgkmcnt(0)
	v_mfma_f32_32x32x16_bf16 v[112:127], v[180:183], v[176:179], v[112:127]
	v_add_u32_e32 v176, v248, v218
	ds_read_b128 v[176:179], v176
	s_waitcnt lgkmcnt(0)
	v_mfma_f32_32x32x16_bf16 v[112:127], v[176:179], v[172:175], v[112:127]
	v_add_u32_e32 v172, v248, v219
	ds_read_b128 v[172:175], v172
	s_waitcnt lgkmcnt(0)
	v_mfma_f32_32x32x16_bf16 v[112:127], v[172:175], v[168:171], v[112:127]
	v_add_u32_e32 v168, v248, v220
	ds_read_b128 v[168:171], v168
	s_waitcnt lgkmcnt(0)
	v_mfma_f32_32x32x16_bf16 v[112:127], v[168:171], v[164:167], v[112:127]
	v_add_u32_e32 v164, v248, v221
	ds_read_b128 v[164:167], v164
	s_waitcnt lgkmcnt(0)
	v_mfma_f32_32x32x16_bf16 v[112:127], v[164:167], v[160:163], v[112:127]
	v_add_u32_e32 v160, v248, v237
	ds_read_b128 v[160:163], v160
	s_waitcnt lgkmcnt(0)
	v_mfma_f32_32x32x16_bf16 v[112:127], v[160:163], v[156:159], v[112:127]
	v_add_u32_e32 v156, v248, v238
	ds_read_b128 v[156:159], v156
	s_waitcnt lgkmcnt(0)
	v_mfma_f32_32x32x16_bf16 v[112:127], v[156:159], v[152:155], v[112:127]
	v_add_u32_e32 v152, v248, v239
	ds_read_b128 v[152:155], v152
	s_waitcnt lgkmcnt(0)
	v_mfma_f32_32x32x16_bf16 v[112:127], v[152:155], v[148:151], v[112:127]
	v_add_u32_e32 v148, v248, v240
	ds_read_b128 v[148:151], v148
	s_waitcnt lgkmcnt(0)
	v_mfma_f32_32x32x16_bf16 v[112:127], v[148:151], v[144:147], v[112:127]
	v_add_u32_e32 v144, v248, v241
	ds_read_b128 v[144:147], v144
	s_waitcnt lgkmcnt(0)
	v_mfma_f32_32x32x16_bf16 v[112:127], v[144:147], v[140:143], v[112:127]
	v_add_u32_e32 v140, v248, v242
	ds_read_b128 v[140:143], v140
	s_waitcnt lgkmcnt(0)
	v_mfma_f32_32x32x16_bf16 v[112:127], v[140:143], v[136:139], v[112:127]
	v_add_u32_e32 v136, v248, v243
	ds_read_b128 v[136:139], v136
	s_waitcnt lgkmcnt(0)
	v_mfma_f32_32x32x16_bf16 v[112:127], v[136:139], v[132:135], v[112:127]
	v_add_u32_e32 v132, v248, v244
	ds_read_b128 v[132:135], v132
	s_waitcnt lgkmcnt(0)
	v_mfma_f32_32x32x16_bf16 v[112:127], v[132:135], v[128:131], v[112:127]
	s_nop 7
	s_waitcnt vmcnt(0) lgkmcnt(0)
	v_lshl_add_u64 v[140:141], v[188:189], 0, s[0:1]
	v_lshl_add_u64 v[142:143], v[190:191], 0, s[0:1]
	v_lshl_add_u64 v[144:145], v[192:193], 0, s[0:1]
	v_lshl_add_u64 v[146:147], v[194:195], 0, s[0:1]
	s_mov_b64 s[0:1], 0
	s_waitcnt lgkmcnt(0)
	s_barrier
; __device__ __forceinline__ float shx(float v, int lane, int mask) { return __builtin_bit_cast(float, __builtin_amdgcn_ds_bpermute((lane ^ mask) << 2, __builtin_bit_cast(int, v))); }
; __device__ __forceinline__ void glds16(const void* gsrc, LAS unsigned char* dst_uniform) { __builtin_amdgcn_global_load_lds((const unsigned*)gsrc, (LAS unsigned*)dst_uniform, 16, 0, 0); }
; __device__ __forceinline__ void xattn_unit(LAS unsigned char* lds, const bf16_t* Qx, const bf16_t* KV, int li, int b, int h, int qb, bf16_t* XO, const int tid) {
;     ...
;     float m = S[0][0];
; #pragma unroll
;     for (int kt = 0; kt < 8; ++kt)
; #pragma unroll
;         for (int r = 0; r < 16; ++r) m = fmaxf(m, S[kt][r]);
;     m = fmaxf(m, pg8::shx(m, lane, 32));
;     float l = 0.f;
; #pragma unroll
;     for (int kt = 0; kt < 8; ++kt)
; #pragma unroll
;         for (int r = 0; r < 16; ++r) { const float p = __builtin_amdgcn_exp2f(S[kt][r] - m); S[kt][r] = p; l += p; }
;     ...
;     const bf16_t* Vb = Kb + 1024;
; #pragma unroll 4
;     for (int ii = 0; ii < 16; ++ii) { const int i = wid * 16 + ii, d0 = i >> 4, ks = i & 15, key = 16 * ks + 8 * hi + ((lane >> 2) & 7), cc = lane & 3;
;         glds16(Vb + (size_t)key * 8192 + 32 * d0 + 8 * cc, lds + i * 1024); }
.Lxa_vdma:
	v_lshl_add_u64 v[148:149], v[146:147], 0, s[0:1]
	s_mov_b32 m0, s24
	s_nop 0
	global_load_lds_dwordx4 v[148:149], off
	v_lshl_add_u64 v[148:149], v[144:145], 0, s[0:1]
	s_add_i32 m0, s24, 0x400
	s_nop 0
	global_load_lds_dwordx4 v[148:149], off
	v_lshl_add_u64 v[148:149], v[142:143], 0, s[0:1]
	s_add_i32 m0, s24, 0x800
	s_nop 0
	global_load_lds_dwordx4 v[148:149], off
	v_lshl_add_u64 v[148:149], v[140:141], 0, s[0:1]
	s_add_i32 m0, s24, 0xc00
	s_add_u32 s0, s0, 0x100000
	global_load_lds_dwordx4 v[148:149], off
	s_addc_u32 s1, s1, 0
	s_addk_i32 s24, 0x1000
	s_cmp_eq_u32 s0, 0x400000
	s_cbranch_scc0 .Lxa_vdma
	v_max_f32_e32 v128, v1, v1
	v_max_f32_e32 v129, v0, v0
	v_max_f32_e32 v128, v129, v128
	v_max3_f32 v128, v128, v2, v3
	v_max3_f32 v128, v128, v4, v5
	v_max3_f32 v128, v128, v6, v7
	v_max3_f32 v128, v128, v8, v9
	v_max3_f32 v128, v128, v10, v11
	v_max3_f32 v128, v128, v12, v13
	v_max3_f32 v128, v128, v14, v15
	v_max3_f32 v128, v128, v16, v17
	v_max3_f32 v128, v128, v18, v19
	v_max3_f32 v128, v128, v20, v21
	v_max3_f32 v128, v128, v22, v23
	v_max3_f32 v128, v128, v24, v25
	v_max3_f32 v128, v128, v26, v27
	v_max3_f32 v128, v128, v28, v29
	v_max3_f32 v128, v128, v30, v31
	v_max3_f32 v128, v128, v48, v49
	v_max3_f32 v128, v128, v50, v51
	v_max3_f32 v128, v128, v52, v53
	v_max3_f32 v128, v128, v54, v55
	v_max3_f32 v128, v128, v56, v57
	v_max3_f32 v128, v128, v58, v59
	v_max3_f32 v128, v128, v60, v61
	v_max3_f32 v128, v128, v62, v63
	v_max3_f32 v128, v128, v32, v33
	v_max3_f32 v128, v128, v34, v35
	v_max3_f32 v128, v128, v36, v37
	v_max3_f32 v128, v128, v38, v39
	v_max3_f32 v128, v128, v40, v41
	v_max3_f32 v128, v128, v42, v43
	v_max3_f32 v128, v128, v44, v45
	v_max3_f32 v128, v128, v46, v47
	v_max3_f32 v128, v128, v64, v65
	v_max3_f32 v128, v128, v66, v67
	v_max3_f32 v128, v128, v68, v69
	v_max3_f32 v128, v128, v70, v71
	v_max3_f32 v128, v128, v72, v73
	v_max3_f32 v128, v128, v74, v75
	v_max3_f32 v128, v128, v76, v77
	v_max3_f32 v128, v128, v78, v79
	v_max3_f32 v128, v128, v80, v81
	v_max3_f32 v128, v128, v82, v83
	v_max3_f32 v128, v128, v84, v85
	v_max3_f32 v128, v128, v86, v87
	v_max3_f32 v128, v128, v88, v89
	v_max3_f32 v128, v128, v90, v91
	v_max3_f32 v128, v128, v92, v93
	v_max3_f32 v128, v128, v94, v95
	v_max3_f32 v128, v128, v96, v97
	v_max3_f32 v128, v128, v98, v99
	v_max3_f32 v128, v128, v100, v101
	v_max3_f32 v128, v128, v102, v103
	v_max3_f32 v128, v128, v104, v105
	v_max3_f32 v128, v128, v106, v107
	v_max3_f32 v128, v128, v108, v109
	v_max3_f32 v128, v128, v110, v111
	v_max3_f32 v128, v128, v112, v113
	v_max3_f32 v128, v128, v114, v115
	v_max3_f32 v128, v128, v116, v117
	v_max3_f32 v128, v128, v118, v119
	v_max3_f32 v128, v128, v120, v121
	v_max3_f32 v128, v128, v122, v123
	v_max3_f32 v128, v128, v124, v125
	v_max3_f32 v128, v128, v126, v127
	ds_bpermute_b32 v129, v249, v128
	s_waitcnt lgkmcnt(0)
	v_max_f32_e32 v129, v129, v129
	v_max_f32_e32 v128, v128, v129
	v_sub_f32_e32 v0, v0, v128
	v_exp_f32_e32 v0, v0
	v_sub_f32_e32 v1, v1, v128
	v_exp_f32_e32 v1, v1
	v_sub_f32_e32 v2, v2, v128
	v_exp_f32_e32 v2, v2
	v_sub_f32_e32 v3, v3, v128
	v_exp_f32_e32 v3, v3
	v_sub_f32_e32 v4, v4, v128
	v_add_f32_e32 v129, 0, v0
	v_exp_f32_e32 v4, v4
	v_sub_f32_e32 v5, v5, v128
	v_add_f32_e32 v129, v1, v129
	v_exp_f32_e32 v5, v5
	v_sub_f32_e32 v6, v6, v128
	v_add_f32_e32 v129, v2, v129
	v_exp_f32_e32 v6, v6
	v_sub_f32_e32 v7, v7, v128
	v_add_f32_e32 v129, v3, v129
	v_exp_f32_e32 v7, v7
	v_sub_f32_e32 v8, v8, v128
	v_add_f32_e32 v129, v4, v129
	v_exp_f32_e32 v8, v8
	v_sub_f32_e32 v9, v9, v128
	v_add_f32_e32 v129, v5, v129
	v_exp_f32_e32 v9, v9
	v_sub_f32_e32 v10, v10, v128
	v_add_f32_e32 v129, v6, v129
	v_exp_f32_e32 v10, v10
	v_sub_f32_e32 v11, v11, v128
	v_add_f32_e32 v129, v7, v129
	v_exp_f32_e32 v11, v11
	v_sub_f32_e32 v12, v12, v128
	v_add_f32_e32 v129, v8, v129
	v_exp_f32_e32 v12, v12
	v_sub_f32_e32 v13, v13, v128
	v_add_f32_e32 v129, v9, v129
	v_exp_f32_e32 v13, v13
	v_sub_f32_e32 v14, v14, v128
	v_add_f32_e32 v129, v10, v129
	v_exp_f32_e32 v14, v14
	v_sub_f32_e32 v15, v15, v128
	v_add_f32_e32 v129, v11, v129
	v_exp_f32_e32 v15, v15
	v_add_f32_e32 v129, v12, v129
	v_add_f32_e32 v129, v13, v129
	v_add_f32_e32 v129, v14, v129
	v_sub_f32_e32 v16, v16, v128
	v_add_f32_e32 v130, v15, v129
	v_exp_f32_e32 v129, v16
	v_sub_f32_e32 v17, v17, v128
	v_add_f32_e32 v16, v129, v130
	v_exp_f32_e32 v130, v17
	v_sub_f32_e32 v17, v18, v128
	v_exp_f32_e32 v131, v17
	v_sub_f32_e32 v17, v19, v128
	v_exp_f32_e32 v132, v17
	v_sub_f32_e32 v17, v20, v128
	v_exp_f32_e32 v133, v17
	v_sub_f32_e32 v17, v21, v128
	v_add_f32_e32 v16, v130, v16
	v_exp_f32_e32 v134, v17
	v_sub_f32_e32 v17, v22, v128
	v_add_f32_e32 v16, v131, v16
	v_exp_f32_e32 v135, v17
	v_sub_f32_e32 v17, v23, v128
	v_add_f32_e32 v16, v132, v16
	v_exp_f32_e32 v136, v17
	v_sub_f32_e32 v17, v24, v128
	v_add_f32_e32 v16, v133, v16
	v_exp_f32_e32 v137, v17
	v_sub_f32_e32 v17, v25, v128
	v_add_f32_e32 v16, v134, v16
	v_exp_f32_e32 v138, v17
	v_sub_f32_e32 v17, v26, v128
	v_add_f32_e32 v16, v135, v16
	v_exp_f32_e32 v139, v17
	v_sub_f32_e32 v17, v27, v128
	v_add_f32_e32 v16, v136, v16
	v_exp_f32_e32 v140, v17
	v_sub_f32_e32 v17, v28, v128
	v_add_f32_e32 v16, v137, v16
	v_exp_f32_e32 v141, v17
	v_sub_f32_e32 v17, v29, v128
	v_add_f32_e32 v16, v138, v16
	v_exp_f32_e32 v142, v17
	v_sub_f32_e32 v17, v30, v128
	v_add_f32_e32 v16, v139, v16
	v_exp_f32_e32 v143, v17
	v_sub_f32_e32 v17, v31, v128
	v_add_f32_e32 v16, v140, v16
	v_exp_f32_e32 v31, v17
	v_sub_f32_e32 v17, v48, v128
	v_add_f32_e32 v16, v141, v16
	v_exp_f32_e32 v48, v17
	v_sub_f32_e32 v17, v49, v128
	v_add_f32_e32 v16, v142, v16
	v_exp_f32_e32 v49, v17
; __device__ __forceinline__ void xattn_unit(LAS unsigned char* lds, const bf16_t* Qx, const bf16_t* KV, int li, int b, int h, int qb, bf16_t* XO, const int tid) {
;     ...
;     for (int kt = 0; kt < 8; ++kt)
; #pragma unroll
;         for (int r = 0; r < 16; ++r) { const float p = __builtin_amdgcn_exp2f(S[kt][r] - m); S[kt][r] = p; l += p; }
	v_sub_f32_e32 v17, v50, v128
	v_add_f32_e32 v16, v143, v16
	v_exp_f32_e32 v50, v17
	v_sub_f32_e32 v17, v51, v128
	v_add_f32_e32 v16, v31, v16
	v_exp_f32_e32 v51, v17
	v_sub_f32_e32 v17, v52, v128
	v_add_f32_e32 v16, v48, v16
	v_exp_f32_e32 v52, v17
	v_sub_f32_e32 v17, v53, v128
	v_add_f32_e32 v16, v49, v16
	v_exp_f32_e32 v53, v17
	v_sub_f32_e32 v17, v54, v128
	v_add_f32_e32 v16, v50, v16
	v_exp_f32_e32 v54, v17
	v_sub_f32_e32 v17, v55, v128
	v_add_f32_e32 v16, v51, v16
	v_exp_f32_e32 v55, v17
	v_sub_f32_e32 v17, v56, v128
	v_add_f32_e32 v16, v52, v16
	v_exp_f32_e32 v56, v17
	v_sub_f32_e32 v17, v57, v128
	v_add_f32_e32 v16, v53, v16
	v_exp_f32_e32 v57, v17
	v_sub_f32_e32 v17, v58, v128
	v_add_f32_e32 v16, v54, v16
	v_exp_f32_e32 v58, v17
	v_sub_f32_e32 v17, v59, v128
	v_add_f32_e32 v16, v55, v16
	v_exp_f32_e32 v59, v17
	v_sub_f32_e32 v17, v60, v128
	v_add_f32_e32 v16, v56, v16
	v_exp_f32_e32 v60, v17
	v_sub_f32_e32 v17, v61, v128
	v_add_f32_e32 v16, v57, v16
	v_exp_f32_e32 v61, v17
	v_sub_f32_e32 v17, v62, v128
	v_add_f32_e32 v16, v58, v16
	v_exp_f32_e32 v62, v17
	v_sub_f32_e32 v17, v63, v128
	v_add_f32_e32 v16, v59, v16
	v_exp_f32_e32 v63, v17
	v_sub_f32_e32 v17, v32, v128
	v_add_f32_e32 v16, v60, v16
	v_exp_f32_e32 v144, v17
	v_sub_f32_e32 v17, v33, v128
	v_add_f32_e32 v16, v61, v16
	v_exp_f32_e32 v145, v17
	v_sub_f32_e32 v17, v34, v128
	v_add_f32_e32 v16, v62, v16
	v_exp_f32_e32 v146, v17
	v_sub_f32_e32 v17, v35, v128
	v_add_f32_e32 v16, v63, v16
	v_exp_f32_e32 v147, v17
	v_sub_f32_e32 v17, v36, v128
	v_add_f32_e32 v16, v144, v16
	v_exp_f32_e32 v148, v17
	v_sub_f32_e32 v17, v37, v128
	v_add_f32_e32 v16, v145, v16
	v_exp_f32_e32 v149, v17
	v_sub_f32_e32 v17, v38, v128
	v_add_f32_e32 v16, v146, v16
	v_exp_f32_e32 v150, v17
	v_sub_f32_e32 v17, v39, v128
	v_add_f32_e32 v16, v147, v16
	v_exp_f32_e32 v151, v17
	v_sub_f32_e32 v17, v40, v128
	v_add_f32_e32 v16, v148, v16
	v_exp_f32_e32 v152, v17
	v_sub_f32_e32 v17, v41, v128
	v_add_f32_e32 v16, v149, v16
	v_exp_f32_e32 v153, v17
	v_sub_f32_e32 v17, v42, v128
	v_add_f32_e32 v16, v150, v16
	v_exp_f32_e32 v154, v17
	v_sub_f32_e32 v17, v43, v128
	v_add_f32_e32 v16, v151, v16
	v_exp_f32_e32 v155, v17
	v_sub_f32_e32 v17, v44, v128
	v_add_f32_e32 v16, v152, v16
	v_exp_f32_e32 v156, v17
	v_sub_f32_e32 v17, v45, v128
	v_add_f32_e32 v16, v153, v16
	v_exp_f32_e32 v157, v17
	v_sub_f32_e32 v17, v46, v128
	v_add_f32_e32 v16, v154, v16
	v_exp_f32_e32 v158, v17
	v_sub_f32_e32 v17, v47, v128
	v_add_f32_e32 v16, v155, v16
	v_exp_f32_e32 v47, v17
	v_sub_f32_e32 v17, v64, v128
	v_add_f32_e32 v16, v156, v16
	v_exp_f32_e32 v64, v17
	v_sub_f32_e32 v17, v65, v128
	v_add_f32_e32 v16, v157, v16
	v_exp_f32_e32 v65, v17
	v_sub_f32_e32 v17, v66, v128
	v_add_f32_e32 v16, v158, v16
	v_exp_f32_e32 v66, v17
	v_sub_f32_e32 v17, v67, v128
	v_add_f32_e32 v16, v47, v16
	v_exp_f32_e32 v67, v17
	v_sub_f32_e32 v17, v68, v128
	v_add_f32_e32 v16, v64, v16
	v_exp_f32_e32 v68, v17
	v_sub_f32_e32 v17, v69, v128
	v_add_f32_e32 v16, v65, v16
	v_exp_f32_e32 v69, v17
	v_sub_f32_e32 v17, v70, v128
	v_add_f32_e32 v16, v66, v16
	v_exp_f32_e32 v70, v17
	v_sub_f32_e32 v17, v71, v128
	v_add_f32_e32 v16, v67, v16
	v_exp_f32_e32 v71, v17
	v_sub_f32_e32 v17, v72, v128
	v_add_f32_e32 v16, v68, v16
	v_exp_f32_e32 v72, v17
	v_sub_f32_e32 v17, v73, v128
	v_add_f32_e32 v16, v69, v16
	v_exp_f32_e32 v73, v17
	v_sub_f32_e32 v17, v74, v128
	v_add_f32_e32 v16, v70, v16
	v_exp_f32_e32 v74, v17
	v_sub_f32_e32 v17, v75, v128
	v_add_f32_e32 v16, v71, v16
	v_exp_f32_e32 v75, v17
	v_sub_f32_e32 v17, v76, v128
	v_add_f32_e32 v16, v72, v16
	v_exp_f32_e32 v76, v17
	v_sub_f32_e32 v17, v77, v128
	v_add_f32_e32 v16, v73, v16
	v_exp_f32_e32 v77, v17
	v_sub_f32_e32 v17, v78, v128
	v_add_f32_e32 v16, v74, v16
	v_exp_f32_e32 v78, v17
	v_sub_f32_e32 v17, v79, v128
	v_add_f32_e32 v16, v75, v16
	v_exp_f32_e32 v79, v17
	v_sub_f32_e32 v17, v80, v128
	v_add_f32_e32 v16, v76, v16
	v_exp_f32_e32 v159, v17
	v_sub_f32_e32 v17, v81, v128
	v_add_f32_e32 v16, v77, v16
	v_exp_f32_e32 v160, v17
	v_sub_f32_e32 v17, v82, v128
	v_add_f32_e32 v16, v78, v16
	v_exp_f32_e32 v82, v17
	v_sub_f32_e32 v17, v83, v128
	v_add_f32_e32 v16, v79, v16
	v_exp_f32_e32 v83, v17
	v_sub_f32_e32 v17, v84, v128
	v_add_f32_e32 v16, v159, v16
	v_exp_f32_e32 v84, v17
	v_sub_f32_e32 v17, v85, v128
	v_add_f32_e32 v16, v160, v16
	v_exp_f32_e32 v85, v17
	v_sub_f32_e32 v17, v86, v128
	v_add_f32_e32 v16, v82, v16
	v_exp_f32_e32 v86, v17
	v_sub_f32_e32 v17, v87, v128
	v_add_f32_e32 v16, v83, v16
	v_exp_f32_e32 v87, v17
	v_sub_f32_e32 v17, v88, v128
	v_add_f32_e32 v16, v84, v16
	v_exp_f32_e32 v88, v17
	v_sub_f32_e32 v17, v89, v128
	v_add_f32_e32 v16, v85, v16
	v_exp_f32_e32 v89, v17
	v_sub_f32_e32 v17, v90, v128
	v_add_f32_e32 v16, v86, v16
	v_exp_f32_e32 v90, v17
	v_sub_f32_e32 v17, v91, v128
	v_add_f32_e32 v16, v87, v16
	v_exp_f32_e32 v91, v17
	v_sub_f32_e32 v17, v92, v128
	v_add_f32_e32 v16, v88, v16
	v_exp_f32_e32 v92, v17
	v_sub_f32_e32 v17, v93, v128
	v_add_f32_e32 v16, v89, v16
	v_exp_f32_e32 v93, v17
	v_sub_f32_e32 v17, v94, v128
	v_add_f32_e32 v16, v90, v16
	v_exp_f32_e32 v94, v17
	v_sub_f32_e32 v17, v95, v128
	v_add_f32_e32 v16, v91, v16
	v_exp_f32_e32 v95, v17
	v_sub_f32_e32 v17, v96, v128
	v_add_f32_e32 v16, v92, v16
	v_exp_f32_e32 v96, v17
	v_sub_f32_e32 v17, v97, v128
; __device__ __forceinline__ float shx(float v, int lane, int mask) { return __builtin_bit_cast(float, __builtin_amdgcn_ds_bpermute((lane ^ mask) << 2, __builtin_bit_cast(int, v))); }
; __device__ __forceinline__ void glds16(const void* gsrc, LAS unsigned char* dst_uniform) { __builtin_amdgcn_global_load_lds((const unsigned*)gsrc, (LAS unsigned*)dst_uniform, 16, 0, 0); }
; #define ATT_SYNC() do { asm volatile("s_waitcnt vmcnt(0) lgkmcnt(0)" ::: "memory"); __syncthreads(); } while (0)
; __device__ __forceinline__ void xattn_unit(LAS unsigned char* lds, const bf16_t* Qx, const bf16_t* KV, int li, int b, int h, int qb, bf16_t* XO, const int tid) {
;     ...
;     for (int kt = 0; kt < 8; ++kt)
; #pragma unroll
;         for (int r = 0; r < 16; ++r) { const float p = __builtin_amdgcn_exp2f(S[kt][r] - m); S[kt][r] = p; l += p; }
;     l += pg8::shx(l, lane, 32);
;     const float inv = __builtin_amdgcn_rcpf(l);
;     bf16x8 pf[16];
; #pragma unroll
;     for (int kt = 0; kt < 8; ++kt) { pf[2 * kt] = pack8(S[kt], 0); pf[2 * kt + 1] = pack8(S[kt], 8); }
;     ATT_SYNC();
;     const bf16_t* Vb = Kb + 1024;
; #pragma unroll 4
;     for (int ii = 0; ii < 16; ++ii) { const int i = wid * 16 + ii, d0 = i >> 4, ks = i & 15, key = 16 * ks + 8 * hi + ((lane >> 2) & 7), cc = lane & 3;
;         glds16(Vb + (size_t)key * 8192 + 32 * d0 + 8 * cc, lds + i * 1024); }
;     ATT_SYNC();
	v_add_f32_e32 v16, v93, v16
	v_exp_f32_e32 v97, v17
	v_sub_f32_e32 v17, v98, v128
	v_add_f32_e32 v16, v94, v16
	v_exp_f32_e32 v98, v17
	v_sub_f32_e32 v17, v99, v128
	v_add_f32_e32 v16, v95, v16
	v_exp_f32_e32 v99, v17
	v_sub_f32_e32 v17, v100, v128
	v_add_f32_e32 v16, v96, v16
	v_exp_f32_e32 v100, v17
	v_sub_f32_e32 v17, v101, v128
	v_add_f32_e32 v16, v97, v16
	v_exp_f32_e32 v101, v17
	v_sub_f32_e32 v17, v102, v128
	v_add_f32_e32 v16, v98, v16
	v_exp_f32_e32 v102, v17
	v_sub_f32_e32 v17, v103, v128
	v_add_f32_e32 v16, v99, v16
	v_exp_f32_e32 v103, v17
	v_sub_f32_e32 v17, v104, v128
	v_add_f32_e32 v16, v100, v16
	v_exp_f32_e32 v104, v17
	v_sub_f32_e32 v17, v105, v128
	v_add_f32_e32 v16, v101, v16
	v_exp_f32_e32 v105, v17
	v_sub_f32_e32 v17, v106, v128
	v_add_f32_e32 v16, v102, v16
	v_exp_f32_e32 v106, v17
	v_sub_f32_e32 v17, v107, v128
	v_add_f32_e32 v16, v103, v16
	v_exp_f32_e32 v107, v17
	v_sub_f32_e32 v17, v108, v128
	v_add_f32_e32 v16, v104, v16
	v_exp_f32_e32 v108, v17
	v_sub_f32_e32 v17, v109, v128
	v_add_f32_e32 v16, v105, v16
	v_exp_f32_e32 v109, v17
	v_sub_f32_e32 v17, v110, v128
	v_add_f32_e32 v16, v106, v16
	v_exp_f32_e32 v110, v17
	v_sub_f32_e32 v17, v111, v128
	v_add_f32_e32 v16, v107, v16
	v_exp_f32_e32 v111, v17
	v_sub_f32_e32 v17, v112, v128
	v_add_f32_e32 v16, v108, v16
	v_exp_f32_e32 v112, v17
	v_sub_f32_e32 v17, v113, v128
	v_add_f32_e32 v16, v109, v16
	v_exp_f32_e32 v113, v17
	v_sub_f32_e32 v17, v114, v128
	v_add_f32_e32 v16, v110, v16
	v_exp_f32_e32 v114, v17
	v_sub_f32_e32 v17, v115, v128
	v_add_f32_e32 v16, v111, v16
	v_exp_f32_e32 v115, v17
	v_sub_f32_e32 v17, v116, v128
	v_add_f32_e32 v16, v112, v16
	v_exp_f32_e32 v116, v17
	v_sub_f32_e32 v17, v117, v128
	v_add_f32_e32 v16, v113, v16
	v_exp_f32_e32 v117, v17
	v_sub_f32_e32 v17, v118, v128
	v_add_f32_e32 v16, v114, v16
	v_exp_f32_e32 v118, v17
	v_sub_f32_e32 v17, v119, v128
	v_add_f32_e32 v16, v115, v16
	v_exp_f32_e32 v119, v17
	v_sub_f32_e32 v17, v120, v128
	v_add_f32_e32 v16, v116, v16
	v_exp_f32_e32 v120, v17
	v_sub_f32_e32 v17, v121, v128
	v_add_f32_e32 v16, v117, v16
	v_exp_f32_e32 v121, v17
	v_sub_f32_e32 v17, v122, v128
	v_add_f32_e32 v16, v118, v16
	v_exp_f32_e32 v122, v17
	v_sub_f32_e32 v17, v123, v128
	v_add_f32_e32 v16, v119, v16
	v_exp_f32_e32 v123, v17
	v_sub_f32_e32 v17, v124, v128
	v_add_f32_e32 v16, v120, v16
	v_exp_f32_e32 v124, v17
	v_sub_f32_e32 v17, v125, v128
	v_add_f32_e32 v16, v121, v16
	v_exp_f32_e32 v125, v17
	v_sub_f32_e32 v17, v126, v128
	v_add_f32_e32 v16, v122, v16
	v_exp_f32_e32 v126, v17
	v_sub_f32_e32 v17, v127, v128
	v_add_f32_e32 v16, v123, v16
	v_exp_f32_e32 v127, v17
	v_add_f32_e32 v16, v124, v16
	v_add_f32_e32 v16, v125, v16
	v_add_f32_e32 v16, v126, v16
	v_add_f32_e32 v80, v127, v16
	ds_bpermute_b32 v81, v249, v80
	v_cvt_pk_bf16_f32 v16, v0, v1
	v_cvt_pk_bf16_f32 v17, v2, v3
	v_cvt_pk_bf16_f32 v18, v4, v5
	v_cvt_pk_bf16_f32 v19, v6, v7
	v_cvt_pk_bf16_f32 v20, v8, v9
	v_cvt_pk_bf16_f32 v21, v10, v11
	v_cvt_pk_bf16_f32 v22, v12, v13
	v_cvt_pk_bf16_f32 v23, v14, v15
	v_cvt_pk_bf16_f32 v24, v129, v130
	v_cvt_pk_bf16_f32 v25, v131, v132
	v_cvt_pk_bf16_f32 v26, v133, v134
	v_cvt_pk_bf16_f32 v27, v135, v136
	v_cvt_pk_bf16_f32 v28, v137, v138
	v_cvt_pk_bf16_f32 v29, v139, v140
	v_cvt_pk_bf16_f32 v30, v141, v142
	v_cvt_pk_bf16_f32 v31, v143, v31
	v_cvt_pk_bf16_f32 v32, v48, v49
	v_cvt_pk_bf16_f32 v33, v50, v51
	v_cvt_pk_bf16_f32 v34, v52, v53
	v_cvt_pk_bf16_f32 v35, v54, v55
	v_cvt_pk_bf16_f32 v36, v56, v57
	v_cvt_pk_bf16_f32 v37, v58, v59
	v_cvt_pk_bf16_f32 v38, v60, v61
	v_cvt_pk_bf16_f32 v39, v62, v63
	v_cvt_pk_bf16_f32 v40, v144, v145
	v_cvt_pk_bf16_f32 v41, v146, v147
	v_cvt_pk_bf16_f32 v42, v148, v149
	v_cvt_pk_bf16_f32 v43, v150, v151
	v_cvt_pk_bf16_f32 v44, v152, v153
	v_cvt_pk_bf16_f32 v45, v154, v155
	v_cvt_pk_bf16_f32 v46, v156, v157
	v_cvt_pk_bf16_f32 v47, v158, v47
	v_cvt_pk_bf16_f32 v48, v64, v65
	v_cvt_pk_bf16_f32 v49, v66, v67
	v_cvt_pk_bf16_f32 v50, v68, v69
	v_cvt_pk_bf16_f32 v51, v70, v71
	v_cvt_pk_bf16_f32 v52, v72, v73
	v_cvt_pk_bf16_f32 v53, v74, v75
	v_cvt_pk_bf16_f32 v54, v76, v77
	v_cvt_pk_bf16_f32 v55, v78, v79
	v_cvt_pk_bf16_f32 v56, v159, v160
	v_cvt_pk_bf16_f32 v57, v82, v83
	v_cvt_pk_bf16_f32 v58, v84, v85
	v_cvt_pk_bf16_f32 v59, v86, v87
	v_cvt_pk_bf16_f32 v60, v88, v89
	v_cvt_pk_bf16_f32 v61, v90, v91
	v_cvt_pk_bf16_f32 v62, v92, v93
	v_cvt_pk_bf16_f32 v63, v94, v95
	v_cvt_pk_bf16_f32 v64, v96, v97
	v_cvt_pk_bf16_f32 v65, v98, v99
	v_cvt_pk_bf16_f32 v66, v100, v101
	v_cvt_pk_bf16_f32 v67, v102, v103
	v_cvt_pk_bf16_f32 v68, v104, v105
	v_cvt_pk_bf16_f32 v69, v106, v107
	v_cvt_pk_bf16_f32 v70, v108, v109
	v_cvt_pk_bf16_f32 v71, v110, v111
	v_cvt_pk_bf16_f32 v72, v112, v113
	v_cvt_pk_bf16_f32 v73, v114, v115
	v_cvt_pk_bf16_f32 v74, v116, v117
	v_cvt_pk_bf16_f32 v75, v118, v119
	v_cvt_pk_bf16_f32 v76, v120, v121
	v_cvt_pk_bf16_f32 v77, v122, v123
	v_cvt_pk_bf16_f32 v78, v124, v125
	v_cvt_pk_bf16_f32 v79, v126, v127
	s_waitcnt lgkmcnt(0)
	v_add_f32_e32 v0, v80, v81
	v_rcp_f32_e32 v82, v0
	s_waitcnt vmcnt(0) lgkmcnt(0)
	v_lshl_add_u64 v[0:1], v[200:201], 1, s[10:11]
	v_lshl_add_u64 v[0:1], s[12:13], 1, v[0:1]
	v_mov_b32_e32 v199, v209
	v_lshl_add_u64 v[80:81], v[0:1], 0, v[198:199]
	s_mov_b32 s0, 0
	s_waitcnt vmcnt(0) lgkmcnt(0)
	s_barrier
